# S_raw phase: each item's Q and K chunks staged through LDS with coalesced row-wise LDS-DMA (1040-byte row pitch), MFMA fragments read from LDS instead of 48 uncoalesced per-lane global loads per wave
# speedup vs baseline: 1.0119x; 1.0119x over previous
.LBB0_767:
	s_or_b64 exec, exec, s[28:29]
	s_and_b32 s24, s0, 0xfffff800
	s_and_b32 s27, s4, 0x7c0
	v_or_b32_e32 v2, s24, v33
	s_or_b32 s28, s27, s24
	v_or_b32_e32 v4, s27, v2
	v_add_u32_e32 v0, s28, v31
	s_and_b32 s28, s37, 3
	v_ashrrev_i32_e32 v5, 31, v4
	s_lshl_b32 s28, s28, 10
	v_lshlrev_b64 v[4:5], 12, v[4:5]
	v_or_b32_e32 v4, s28, v4
	v_or_b32_e32 v2, s24, v32
	v_lshl_add_u64 v[20:21], v[18:19], 0, v[4:5]
	v_or_b32_e32 v4, s27, v2
	v_ashrrev_i32_e32 v5, 31, v4
	v_ashrrev_i32_e32 v1, 31, v0
	v_lshlrev_b64 v[4:5], 12, v[4:5]
	v_lshlrev_b64 v[0:1], 12, v[0:1]
	v_or_b32_e32 v4, s28, v4
	v_or_b32_e32 v0, s28, v0
	v_lshl_add_u64 v[22:23], v[18:19], 0, v[4:5]
	v_mov_b32_e32 v4, 0
	v_lshl_add_u64 v[0:1], v[18:19], 0, v[0:1]
	s_mov_b64 s[28:29], 0
	v_mov_b32_e32 v5, v4
	v_mov_b32_e32 v6, v4
	v_mov_b32_e32 v7, v4
	v_mov_b32_e32 v8, v4
	v_mov_b32_e32 v9, v4
	v_mov_b32_e32 v10, v4
	v_mov_b32_e32 v11, v4
	s_sub_u32 s80, s22, 0x3a20000
	s_subb_u32 s81, s23, 0
	s_and_b32 s82, s26, 31
	s_lshl_b32 s82, s82, 6
	s_lshr_b32 s83, s37, 2
	s_lshl_b32 s83, s83, 11
	s_add_i32 s82, s82, s83
	s_and_b32 s83, s37, 3
	s_lshl_b32 s83, s83, 10
	s_lshl_b32 s84, s82, 12
	s_add_u32 s84, s84, s83
	s_add_u32 s85, s84, 0x21752000
	s_add_u32 s86, s80, s85
	s_addc_u32 s87, s81, 0
	s_add_u32 s85, s84, 0x25b52000
	s_add_u32 s88, s80, s85
	s_addc_u32 s89, s81, 0
	v_lshrrev_b32_e32 v73, 6, v201
	s_nop 0
	v_readfirstlane_b32 s90, v73
	s_lshl_b32 s91, s90, 15
	v_lshlrev_b32_e32 v72, 4, v200
	v_add_u32_e32 v72, s91, v72
	s_mul_i32 s92, s90, 0x2080
	s_add_i32 m0, s92, 0x0
	s_nop 0
	global_load_lds_dwordx4 v72, s[86:87]
	s_add_i32 m0, s92, 0x10400
	s_nop 0
	global_load_lds_dwordx4 v72, s[88:89]
	v_add_u32_e32 v72, 0x1000, v72
	s_add_i32 m0, s92, 0x410
	s_nop 0
	global_load_lds_dwordx4 v72, s[86:87]
	s_add_i32 m0, s92, 0x10810
	s_nop 0
	global_load_lds_dwordx4 v72, s[88:89]
	v_add_u32_e32 v72, 0x1000, v72
	s_add_i32 m0, s92, 0x820
	s_nop 0
	global_load_lds_dwordx4 v72, s[86:87]
	s_add_i32 m0, s92, 0x10c20
	s_nop 0
	global_load_lds_dwordx4 v72, s[88:89]
	v_add_u32_e32 v72, 0x1000, v72
	s_add_i32 m0, s92, 0xc30
	s_nop 0
	global_load_lds_dwordx4 v72, s[86:87]
	s_add_i32 m0, s92, 0x11030
	s_nop 0
	global_load_lds_dwordx4 v72, s[88:89]
	v_add_u32_e32 v72, 0x1000, v72
	s_add_i32 m0, s92, 0x1040
	s_nop 0
	global_load_lds_dwordx4 v72, s[86:87]
	s_add_i32 m0, s92, 0x11440
	s_nop 0
	global_load_lds_dwordx4 v72, s[88:89]
	v_add_u32_e32 v72, 0x1000, v72
	s_add_i32 m0, s92, 0x1450
	s_nop 0
	global_load_lds_dwordx4 v72, s[86:87]
	s_add_i32 m0, s92, 0x11850
	s_nop 0
	global_load_lds_dwordx4 v72, s[88:89]
	v_add_u32_e32 v72, 0x1000, v72
	s_add_i32 m0, s92, 0x1860
	s_nop 0
	global_load_lds_dwordx4 v72, s[86:87]
	s_add_i32 m0, s92, 0x11c60
	s_nop 0
	global_load_lds_dwordx4 v72, s[88:89]
	v_add_u32_e32 v72, 0x1000, v72
	s_add_i32 m0, s92, 0x1c70
	s_nop 0
	global_load_lds_dwordx4 v72, s[86:87]
	s_add_i32 m0, s92, 0x12070
	s_nop 0
	global_load_lds_dwordx4 v72, s[88:89]
	v_and_b32_e32 v172, 15, v200
	v_lshrrev_b32_e32 v73, 4, v200
	v_lshlrev_b32_e32 v73, 4, v73
	s_lshr_b32 s93, s90, 1
	s_lshl_b32 s93, s93, 4
	v_add_u32_e32 v173, s93, v172
	v_mul_u32_u24_e32 v173, 0x410, v173
	s_and_b32 s93, s90, 1
	s_lshl_b32 s93, s93, 5
	s_addk_i32 s93, 0x40
	v_add_u32_e32 v172, s93, v172
	v_mul_u32_u24_e32 v172, 0x410, v172
	v_add_u32_e32 v173, v173, v73
	v_add_u32_e32 v172, v172, v73
	s_waitcnt vmcnt(0)
	s_barrier
	ds_read_b128 v[76:79], v173 offset:0
	ds_read_b128 v[80:83], v172 offset:0
	ds_read_b128 v[84:87], v172 offset:16640
	ds_read_b128 v[88:91], v173 offset:64
	ds_read_b128 v[92:95], v172 offset:64
	ds_read_b128 v[96:99], v172 offset:16704
	ds_read_b128 v[100:103], v173 offset:128
	ds_read_b128 v[104:107], v172 offset:128
	ds_read_b128 v[108:111], v172 offset:16768
	ds_read_b128 v[112:115], v173 offset:192
	ds_read_b128 v[116:119], v172 offset:192
	ds_read_b128 v[120:123], v172 offset:16832
	ds_read_b128 v[124:127], v173 offset:256
	ds_read_b128 v[128:131], v172 offset:256
	ds_read_b128 v[132:135], v172 offset:16896
	ds_read_b128 v[136:139], v173 offset:320
	ds_read_b128 v[140:143], v172 offset:320
	ds_read_b128 v[144:147], v172 offset:16960
	ds_read_b128 v[148:151], v173 offset:384
	ds_read_b128 v[152:155], v172 offset:384
	ds_read_b128 v[156:159], v172 offset:17024
	ds_read_b128 v[160:163], v173 offset:448
	ds_read_b128 v[164:167], v172 offset:448
	ds_read_b128 v[168:171], v172 offset:17088
	s_waitcnt lgkmcnt(0)
	v_mfma_f32_16x16x32_bf16 v[4:7], v[76:79], v[80:83], v[4:7]
	v_mfma_f32_16x16x32_bf16 v[8:11], v[76:79], v[84:87], v[8:11]
	v_mfma_f32_16x16x32_bf16 v[4:7], v[88:91], v[92:95], v[4:7]
	v_mfma_f32_16x16x32_bf16 v[8:11], v[88:91], v[96:99], v[8:11]
	v_mfma_f32_16x16x32_bf16 v[4:7], v[100:103], v[104:107], v[4:7]
	v_mfma_f32_16x16x32_bf16 v[8:11], v[100:103], v[108:111], v[8:11]
	v_mfma_f32_16x16x32_bf16 v[4:7], v[112:115], v[116:119], v[4:7]
	v_mfma_f32_16x16x32_bf16 v[8:11], v[112:115], v[120:123], v[8:11]
	v_mfma_f32_16x16x32_bf16 v[4:7], v[124:127], v[128:131], v[4:7]
	v_mfma_f32_16x16x32_bf16 v[8:11], v[124:127], v[132:135], v[8:11]
	v_mfma_f32_16x16x32_bf16 v[4:7], v[136:139], v[140:143], v[4:7]
	v_mfma_f32_16x16x32_bf16 v[8:11], v[136:139], v[144:147], v[8:11]
	v_mfma_f32_16x16x32_bf16 v[4:7], v[148:151], v[152:155], v[4:7]
	v_mfma_f32_16x16x32_bf16 v[8:11], v[148:151], v[156:159], v[8:11]
	v_mfma_f32_16x16x32_bf16 v[4:7], v[160:163], v[164:167], v[4:7]
	v_mfma_f32_16x16x32_bf16 v[8:11], v[160:163], v[168:171], v[8:11]
	ds_read_b128 v[76:79], v173 offset:512
	ds_read_b128 v[80:83], v172 offset:512
	ds_read_b128 v[84:87], v172 offset:17152
	ds_read_b128 v[88:91], v173 offset:576
	ds_read_b128 v[92:95], v172 offset:576
	ds_read_b128 v[96:99], v172 offset:17216
	ds_read_b128 v[100:103], v173 offset:640
	ds_read_b128 v[104:107], v172 offset:640
	ds_read_b128 v[108:111], v172 offset:17280
	ds_read_b128 v[112:115], v173 offset:704
	ds_read_b128 v[116:119], v172 offset:704
	ds_read_b128 v[120:123], v172 offset:17344
	ds_read_b128 v[124:127], v173 offset:768
	ds_read_b128 v[128:131], v172 offset:768
	ds_read_b128 v[132:135], v172 offset:17408
	ds_read_b128 v[136:139], v173 offset:832
	ds_read_b128 v[140:143], v172 offset:832
	ds_read_b128 v[144:147], v172 offset:17472
	ds_read_b128 v[148:151], v173 offset:896
	ds_read_b128 v[152:155], v172 offset:896
	ds_read_b128 v[156:159], v172 offset:17536
	ds_read_b128 v[160:163], v173 offset:960
	ds_read_b128 v[164:167], v172 offset:960
	ds_read_b128 v[168:171], v172 offset:17600
	s_waitcnt lgkmcnt(0)
	v_mfma_f32_16x16x32_bf16 v[4:7], v[76:79], v[80:83], v[4:7]
	v_mfma_f32_16x16x32_bf16 v[8:11], v[76:79], v[84:87], v[8:11]
	v_mfma_f32_16x16x32_bf16 v[4:7], v[88:91], v[92:95], v[4:7]
	v_mfma_f32_16x16x32_bf16 v[8:11], v[88:91], v[96:99], v[8:11]
	v_mfma_f32_16x16x32_bf16 v[4:7], v[100:103], v[104:107], v[4:7]
	v_mfma_f32_16x16x32_bf16 v[8:11], v[100:103], v[108:111], v[8:11]
	v_mfma_f32_16x16x32_bf16 v[4:7], v[112:115], v[116:119], v[4:7]
	v_mfma_f32_16x16x32_bf16 v[8:11], v[112:115], v[120:123], v[8:11]
	v_mfma_f32_16x16x32_bf16 v[4:7], v[124:127], v[128:131], v[4:7]
	v_mfma_f32_16x16x32_bf16 v[8:11], v[124:127], v[132:135], v[8:11]
	v_mfma_f32_16x16x32_bf16 v[4:7], v[136:139], v[140:143], v[4:7]
	v_mfma_f32_16x16x32_bf16 v[8:11], v[136:139], v[144:147], v[8:11]
	v_mfma_f32_16x16x32_bf16 v[4:7], v[148:151], v[152:155], v[4:7]
	v_mfma_f32_16x16x32_bf16 v[8:11], v[148:151], v[156:159], v[8:11]
	v_mfma_f32_16x16x32_bf16 v[4:7], v[160:163], v[164:167], v[4:7]
	v_mfma_f32_16x16x32_bf16 v[8:11], v[160:163], v[168:171], v[8:11]
	s_barrier
	s_nop 7
	s_ashr_i32 s27, s26, 31
	s_lshl_b64 s[28:29], s[26:27], 14
	v_lshl_add_u64 v[0:1], s[28:29], 0, v[16:17]
	s_add_i32 s26, s26, s52
	s_add_i32 s0, s0, s1
	s_add_i32 s4, s4, s5
	v_lshl_add_u64 v[0:1], v[14:15], 0, v[0:1]
	s_cmpk_gt_i32 s26, 0x3ff
	flat_store_dword v[0:1], v4
	flat_store_dword v[0:1], v5 offset:256
	flat_store_dword v[0:1], v6 offset:512
	flat_store_dword v[0:1], v7 offset:768
	flat_store_dword v[0:1], v8 offset:64
	flat_store_dword v[0:1], v9 offset:320
	flat_store_dword v[0:1], v10 offset:576
	flat_store_dword v[0:1], v11 offset:832
	s_cbranch_scc0 .LBB0_765
